# speedup vs baseline: 1.0307x; 1.0307x over previous
; __device__ __forceinline__ unsigned cvt_pk_bf16(float lo, float hi) { unsigned r; asm volatile("v_cvt_pk_bf16_f32 %0, %1, %2" : "=v"(r) : "v"(lo), "v"(hi)); return r; }
; #define LAS __attribute__((address_space(3)))
; __device__ __forceinline__ float row_rs(const float* ssq, int row, int fq) {
;     float s = 0.f;
; #pragma unroll
;     for (int i = 0; i < 4; ++i) s += ssq[(size_t)(fq * 4 + i) * T + row];
;     s += __shfl_xor(s, 16); s += __shfl_xor(s, 32);
;     return rsqrtf(s * (1.0f / D) + RMS_EPS);
; }
;     __device__ __forceinline__ void operator()(const f32x4 (&acc)[2][2][4][2], const Unit& u, int wr, int wc, int fr, int fq) const {
;         const int lane = fr + 16 * fq, cl = wc * 32 + 8 * fq, c = u.pn * 128 + cl, row0 = u.pm * 256 + wr * 64 + fr;
;         float rs[2][4];
; #pragma unroll
;         for (int ai = 0; ai < 2; ++ai)
; #pragma unroll
;             for (int m = 0; m < 4; ++m) {
;                 rs[ai][m] = row_rs(ssq, row0 + ai * 128 + m * 16, fq);
;                 if (fr >= 14) {
;                     const f32x4 a0 = acc[ai][0][m][0] * rs[ai][m], a1 = acc[ai][0][m][1] * rs[ai][m];
;                     v4u w; w.x = pg8::cvt_pk_bf16(a0[0], a0[1]); w.y = pg8::cvt_pk_bf16(a0[2], a0[3]); w.z = pg8::cvt_pk_bf16(a1[0], a1[1]); w.w = pg8::cvt_pk_bf16(a1[2], a1[3]);
;                     const int grp = ai * 8 + wr * 4 + m;
;                     *(LAS v4u*)(bnd + ((grp * 2 + fr - 14) * 128 + cl) * 2) = w;
;                 }
;             }
.LBB0_92:
	s_lshl_b32 s0, s28, 8
	v_and_b32_e32 v188, 15, v219
	v_lshrrev_b32_e32 v1, 4, v219
	s_add_i32 s0, s0, s65
	v_lshl_add_u32 v100, v1, 3, s70
	v_or_b32_e32 v0, s0, v188
	v_lshlrev_b32_e32 v2, 19, v1
	v_lshlrev_b32_e32 v1, 15, v219
	v_mov_b32_e32 v84, 0x60000
	s_mov_b32 s0, 0x3e0000
	v_cmp_lt_i32_e32 vcc, v225, v220
	v_bitop3_b32 v92, v1, s0, v84 bitop3:0xc8
	v_or_b32_e32 v96, 0x20000, v2
	v_cndmask_b32_e32 v1, v219, v225, vcc
	v_cmp_lt_i32_e32 vcc, v226, v220
	v_lshlrev_b32_e32 v101, 2, v1
	v_mov_b32_e32 v97, v3
	v_cndmask_b32_e32 v1, v219, v226, vcc
	v_lshlrev_b32_e32 v102, 2, v1
	v_ashrrev_i32_e32 v1, 31, v0
	v_lshl_add_u64 v[90:91], v[0:1], 2, s[56:57]
	v_lshl_add_u64 v[84:85], v[90:91], 0, v[2:3]
	v_lshl_add_u64 v[86:87], v[90:91], 0, v[96:97]
	v_or_b32_e32 v94, 0x40000, v2
	v_mov_b32_e32 v95, v3
	v_mov_b32_e32 v93, v3
	v_cmp_gt_u32_e32 vcc, 14, v188
	v_cmp_lt_u32_e64 s[40:41], 13, v188
	v_lshl_add_u32 v103, v188, 8, s10
	v_lshl_add_u64 v[88:89], v[90:91], 0, v[94:95]
	v_lshl_add_u64 v[90:91], v[90:91], 0, v[92:93]
	v_lshl_add_u32 v244, v0, 2, v2
	v_add_u32_e32 v245, 0x20000, v244
	v_add_u32_e32 v246, 0x40000, v244
	v_add_u32_e32 v247, 0x60000, v244
	global_load_dword v112, v244, s[56:57]
	global_load_dword v113, v245, s[56:57]
	global_load_dword v114, v246, s[56:57]
	global_load_dword v115, v247, s[56:57]
	global_load_dword v164, v244, s[56:57] offset:64
	global_load_dword v165, v245, s[56:57] offset:64
	global_load_dword v166, v246, s[56:57] offset:64
	global_load_dword v167, v247, s[56:57] offset:64
	global_load_dword v196, v244, s[56:57] offset:128
	global_load_dword v197, v245, s[56:57] offset:128
	global_load_dword v198, v246, s[56:57] offset:128
	global_load_dword v199, v247, s[56:57] offset:128
	global_load_dword v200, v244, s[56:57] offset:192
	global_load_dword v201, v245, s[56:57] offset:192
	global_load_dword v202, v246, s[56:57] offset:192
	global_load_dword v203, v247, s[56:57] offset:192
	global_load_dword v206, v244, s[56:57] offset:512
	global_load_dword v207, v245, s[56:57] offset:512
	global_load_dword v208, v246, s[56:57] offset:512
	global_load_dword v209, v247, s[56:57] offset:512
	global_load_dword v210, v244, s[56:57] offset:576
	global_load_dword v211, v245, s[56:57] offset:576
	global_load_dword v212, v246, s[56:57] offset:576
	global_load_dword v213, v247, s[56:57] offset:576
	global_load_dword v214, v244, s[56:57] offset:640
	global_load_dword v215, v245, s[56:57] offset:640
	global_load_dword v234, v246, s[56:57] offset:640
	global_load_dword v239, v247, s[56:57] offset:640
	global_load_dword v240, v244, s[56:57] offset:704
	global_load_dword v241, v245, s[56:57] offset:704
	global_load_dword v242, v246, s[56:57] offset:704
	global_load_dword v243, v247, s[56:57] offset:704
	s_waitcnt vmcnt(0)
	v_add_f32_e32 v112, v112, v113
	v_add_f32_e32 v164, v164, v165
	v_add_f32_e32 v196, v196, v197
	v_add_f32_e32 v200, v200, v201
	v_add_f32_e32 v206, v206, v207
	v_add_f32_e32 v210, v210, v211
	v_add_f32_e32 v214, v214, v215
	v_add_f32_e32 v240, v240, v241
	v_add_f32_e32 v112, v112, v114
	v_add_f32_e32 v164, v164, v166
	v_add_f32_e32 v196, v196, v198
	v_add_f32_e32 v200, v200, v202
	v_add_f32_e32 v206, v206, v208
	v_add_f32_e32 v210, v210, v212
	v_add_f32_e32 v214, v214, v234
	v_add_f32_e32 v240, v240, v242
	v_add_f32_e32 v112, v112, v115
	v_add_f32_e32 v164, v164, v167
	v_add_f32_e32 v196, v196, v199
	v_add_f32_e32 v200, v200, v203
	v_add_f32_e32 v206, v206, v209
	v_add_f32_e32 v210, v210, v213
	v_add_f32_e32 v214, v214, v239
	v_add_f32_e32 v240, v240, v243
	ds_bpermute_b32 v113, v101, v112
	ds_bpermute_b32 v165, v101, v164
	ds_bpermute_b32 v197, v101, v196
	ds_bpermute_b32 v201, v101, v200
	ds_bpermute_b32 v207, v101, v206
	ds_bpermute_b32 v211, v101, v210
	ds_bpermute_b32 v215, v101, v214
	ds_bpermute_b32 v241, v101, v240
	s_waitcnt lgkmcnt(0)
	v_add_f32_e32 v112, v112, v113
	v_add_f32_e32 v164, v164, v165
	v_add_f32_e32 v196, v196, v197
	v_add_f32_e32 v200, v200, v201
	v_add_f32_e32 v206, v206, v207
	v_add_f32_e32 v210, v210, v211
	v_add_f32_e32 v214, v214, v215
	v_add_f32_e32 v240, v240, v241
	ds_bpermute_b32 v113, v102, v112
	ds_bpermute_b32 v165, v102, v164
	ds_bpermute_b32 v197, v102, v196
	ds_bpermute_b32 v201, v102, v200
	ds_bpermute_b32 v207, v102, v206
	ds_bpermute_b32 v211, v102, v210
	ds_bpermute_b32 v215, v102, v214
	ds_bpermute_b32 v241, v102, v240
	s_waitcnt lgkmcnt(0)
	v_add_f32_e32 v112, v112, v113
	v_add_f32_e32 v164, v164, v165
	v_add_f32_e32 v196, v196, v197
	v_add_f32_e32 v200, v200, v201
	v_add_f32_e32 v206, v206, v207
	v_add_f32_e32 v210, v210, v211
	v_add_f32_e32 v214, v214, v215
	v_add_f32_e32 v240, v240, v241
	v_fmamk_f32 v1, v112, 0x3a800000, v217
	v_cmp_gt_f32_e64 s[0:1], s33, v1
	v_mul_f32_e32 v98, 0x4b800000, v1
	s_nop 0
	v_cndmask_b32_e64 v1, v1, v98, s[0:1]
	v_rsq_f32_e32 v1, v1
	s_nop 0
	v_mul_f32_e32 v98, 0x45800000, v1
	v_cndmask_b32_e64 v204, v1, v98, s[0:1]
	v_lshlrev_b32_e32 v1, 1, v100
	s_and_saveexec_b64 s[0:1], s[40:41]
	s_cbranch_execz .LBB0_94
	v_pk_mul_f32 v[98:99], v[162:163], v[204:205] op_sel_hi:[1,0]
	v_pk_mul_f32 v[104:105], v[160:161], v[204:205] op_sel_hi:[1,0]
	s_movk_i32 s16, 0xf200
	v_cvt_pk_bf16_f32 v104, v104, v105
	v_cvt_pk_bf16_f32 v105, v98, v99
	v_lshlrev_b32_e32 v98, 1, v100
	v_pk_mul_f32 v[106:107], v[156:157], v[204:205] op_sel_hi:[1,0]
	v_add3_u32 v98, v103, v98, s16
	v_pk_mul_f32 v[108:109], v[158:159], v[204:205] op_sel_hi:[1,0]
	v_cvt_pk_bf16_f32 v106, v106, v107
	s_nop 0
	v_cvt_pk_bf16_f32 v107, v108, v109
	ds_write_b128 v98, v[104:107]
; __device__ __forceinline__ unsigned cvt_pk_bf16(float lo, float hi) { unsigned r; asm volatile("v_cvt_pk_bf16_f32 %0, %1, %2" : "=v"(r) : "v"(lo), "v"(hi)); return r; }
; #define LAS __attribute__((address_space(3)))
; __device__ __forceinline__ float row_rs(const float* ssq, int row, int fq) {
;     float s = 0.f;
; #pragma unroll
;     for (int i = 0; i < 4; ++i) s += ssq[(size_t)(fq * 4 + i) * T + row];
;     s += __shfl_xor(s, 16); s += __shfl_xor(s, 32);
;     return rsqrtf(s * (1.0f / D) + RMS_EPS);
; }
;     __device__ __forceinline__ void operator()(const f32x4 (&acc)[2][2][4][2], const Unit& u, int wr, int wc, int fr, int fq) const {
;         const int lane = fr + 16 * fq, cl = wc * 32 + 8 * fq, c = u.pn * 128 + cl, row0 = u.pm * 256 + wr * 64 + fr;
;         float rs[2][4];
; #pragma unroll
;         for (int ai = 0; ai < 2; ++ai)
; #pragma unroll
;             for (int m = 0; m < 4; ++m) {
;                 rs[ai][m] = row_rs(ssq, row0 + ai * 128 + m * 16, fq);
;                 if (fr >= 14) {
;                     const f32x4 a0 = acc[ai][0][m][0] * rs[ai][m], a1 = acc[ai][0][m][1] * rs[ai][m];
;                     v4u w; w.x = pg8::cvt_pk_bf16(a0[0], a0[1]); w.y = pg8::cvt_pk_bf16(a0[2], a0[3]); w.z = pg8::cvt_pk_bf16(a1[0], a1[1]); w.w = pg8::cvt_pk_bf16(a1[2], a1[3]);
;                     const int grp = ai * 8 + wr * 4 + m;
;                     *(LAS v4u*)(bnd + ((grp * 2 + fr - 14) * 128 + cl) * 2) = w;
;                 }
;             }
.LBB0_94:
	s_or_b64 exec, exec, s[0:1]
	v_or_b32_e32 v184, 16, v0
	v_ashrrev_i32_e32 v185, 31, v184
	v_lshl_add_u64 v[98:99], s[56:57], 0, v[2:3]
	v_lshlrev_b64 v[104:105], 2, v[184:185]
	v_lshl_add_u64 v[106:107], v[98:99], 0, v[104:105]
	v_lshl_add_u64 v[96:97], s[56:57], 0, v[96:97]
	v_lshl_add_u64 v[106:107], v[96:97], 0, v[104:105]
	v_lshl_add_u64 v[94:95], s[56:57], 0, v[94:95]
	v_lshl_add_u64 v[92:93], s[56:57], 0, v[92:93]
	v_lshl_add_u64 v[106:107], v[94:95], 0, v[104:105]
	v_lshl_add_u64 v[104:105], v[92:93], 0, v[104:105]
	v_fmamk_f32 v2, v164, 0x3a800000, v217
	v_cmp_gt_f32_e64 s[0:1], s33, v2
	v_mul_f32_e32 v104, 0x4b800000, v2
	s_nop 0
	v_cndmask_b32_e64 v2, v2, v104, s[0:1]
	v_rsq_f32_e32 v2, v2
	s_nop 0
	v_mul_f32_e32 v104, 0x45800000, v2
	v_cndmask_b32_e64 v190, v2, v104, s[0:1]
	s_and_saveexec_b64 s[0:1], s[40:41]
	s_cbranch_execz .LBB0_96
	v_lshlrev_b32_e32 v2, 1, v100
	s_movk_i32 s16, 0xf400
	v_pk_mul_f32 v[106:107], v[146:147], v[190:191] op_sel_hi:[1,0]
	v_pk_mul_f32 v[104:105], v[144:145], v[190:191] op_sel_hi:[1,0]
	v_add3_u32 v2, v103, v2, s16
	v_pk_mul_f32 v[108:109], v[142:143], v[190:191] op_sel_hi:[1,0]
	v_pk_mul_f32 v[110:111], v[140:141], v[190:191] op_sel_hi:[1,0]
	v_cvt_pk_bf16_f32 v104, v104, v105
	v_cvt_pk_bf16_f32 v105, v106, v107
	s_nop 0
	v_cvt_pk_bf16_f32 v106, v110, v111
	v_cvt_pk_bf16_f32 v107, v108, v109
	ds_write_b128 v2, v[104:107]
.LBB0_96:
	s_or_b64 exec, exec, s[0:1]
	v_or_b32_e32 v180, 32, v0
	v_ashrrev_i32_e32 v181, 31, v180
	v_lshlrev_b64 v[104:105], 2, v[180:181]
	v_lshl_add_u64 v[106:107], v[98:99], 0, v[104:105]
	v_lshl_add_u64 v[106:107], v[96:97], 0, v[104:105]
	v_lshl_add_u64 v[106:107], v[94:95], 0, v[104:105]
	v_lshl_add_u64 v[104:105], v[92:93], 0, v[104:105]
	v_fmamk_f32 v2, v196, 0x3a800000, v217
	v_cmp_gt_f32_e64 s[0:1], s33, v2
	v_mul_f32_e32 v104, 0x4b800000, v2
	s_nop 0
	v_cndmask_b32_e64 v2, v2, v104, s[0:1]
	v_rsq_f32_e32 v2, v2
	s_nop 0
	v_mul_f32_e32 v104, 0x45800000, v2
	v_cndmask_b32_e64 v186, v2, v104, s[0:1]
	s_and_saveexec_b64 s[0:1], s[40:41]
	s_cbranch_execz .LBB0_98
	v_lshlrev_b32_e32 v2, 1, v100
	s_movk_i32 s16, 0xf600
	v_pk_mul_f32 v[106:107], v[130:131], v[186:187] op_sel_hi:[1,0]
	v_pk_mul_f32 v[104:105], v[128:129], v[186:187] op_sel_hi:[1,0]
	v_add3_u32 v2, v103, v2, s16
	v_pk_mul_f32 v[108:109], v[126:127], v[186:187] op_sel_hi:[1,0]
	v_pk_mul_f32 v[110:111], v[124:125], v[186:187] op_sel_hi:[1,0]
	v_cvt_pk_bf16_f32 v104, v104, v105
	v_cvt_pk_bf16_f32 v105, v106, v107
	s_nop 0
	v_cvt_pk_bf16_f32 v106, v110, v111
	v_cvt_pk_bf16_f32 v107, v108, v109
	ds_write_b128 v2, v[104:107]
.LBB0_98:
	s_or_b64 exec, exec, s[0:1]
	v_or_b32_e32 v178, 48, v0
	v_ashrrev_i32_e32 v179, 31, v178
	v_lshlrev_b64 v[104:105], 2, v[178:179]
	v_lshl_add_u64 v[98:99], v[98:99], 0, v[104:105]
	v_lshl_add_u64 v[96:97], v[96:97], 0, v[104:105]
	v_lshl_add_u64 v[94:95], v[94:95], 0, v[104:105]
	v_lshl_add_u64 v[92:93], v[92:93], 0, v[104:105]
	v_fmamk_f32 v2, v200, 0x3a800000, v217
	v_mul_f32_e32 v92, 0x4b800000, v2
	v_cmp_gt_f32_e64 s[0:1], s33, v2
	s_nop 1
	v_cndmask_b32_e64 v2, v2, v92, s[0:1]
	v_rsq_f32_e32 v2, v2
	s_nop 0
	v_mul_f32_e32 v92, 0x45800000, v2
	v_cndmask_b32_e64 v182, v2, v92, s[0:1]
	s_and_saveexec_b64 s[0:1], s[40:41]
	s_cbranch_execz .LBB0_100
	v_lshlrev_b32_e32 v2, 1, v100
	s_movk_i32 s16, 0xf800
	v_pk_mul_f32 v[94:95], v[82:83], v[182:183] op_sel_hi:[1,0]
	v_pk_mul_f32 v[92:93], v[80:81], v[182:183] op_sel_hi:[1,0]
	v_add3_u32 v2, v103, v2, s16
	v_pk_mul_f32 v[96:97], v[78:79], v[182:183] op_sel_hi:[1,0]
	v_pk_mul_f32 v[98:99], v[76:77], v[182:183] op_sel_hi:[1,0]
	v_cvt_pk_bf16_f32 v92, v92, v93
	v_cvt_pk_bf16_f32 v93, v94, v95
	s_nop 0
	v_cvt_pk_bf16_f32 v94, v98, v99
	v_cvt_pk_bf16_f32 v95, v96, v97
	ds_write_b128 v2, v[92:95]
; __device__ __forceinline__ unsigned cvt_pk_bf16(float lo, float hi) { unsigned r; asm volatile("v_cvt_pk_bf16_f32 %0, %1, %2" : "=v"(r) : "v"(lo), "v"(hi)); return r; }
; #define LAS __attribute__((address_space(3)))
; __device__ __forceinline__ float row_rs(const float* ssq, int row, int fq) {
;     float s = 0.f;
; #pragma unroll
;     for (int i = 0; i < 4; ++i) s += ssq[(size_t)(fq * 4 + i) * T + row];
;     s += __shfl_xor(s, 16); s += __shfl_xor(s, 32);
;     return rsqrtf(s * (1.0f / D) + RMS_EPS);
; }
;     __device__ __forceinline__ void operator()(const f32x4 (&acc)[2][2][4][2], const Unit& u, int wr, int wc, int fr, int fq) const {
;         const int lane = fr + 16 * fq, cl = wc * 32 + 8 * fq, c = u.pn * 128 + cl, row0 = u.pm * 256 + wr * 64 + fr;
;         float rs[2][4];
; #pragma unroll
;         for (int ai = 0; ai < 2; ++ai)
; #pragma unroll
;             for (int m = 0; m < 4; ++m) {
;                 rs[ai][m] = row_rs(ssq, row0 + ai * 128 + m * 16, fq);
;                 if (fr >= 14) {
;                     const f32x4 a0 = acc[ai][0][m][0] * rs[ai][m], a1 = acc[ai][0][m][1] * rs[ai][m];
;                     v4u w; w.x = pg8::cvt_pk_bf16(a0[0], a0[1]); w.y = pg8::cvt_pk_bf16(a0[2], a0[3]); w.z = pg8::cvt_pk_bf16(a1[0], a1[1]); w.w = pg8::cvt_pk_bf16(a1[2], a1[3]);
;                     const int grp = ai * 8 + wr * 4 + m;
;                     *(LAS v4u*)(bnd + ((grp * 2 + fr - 14) * 128 + cl) * 2) = w;
;                 }
;             }
.LBB0_100:
	s_or_b64 exec, exec, s[0:1]
	v_fmamk_f32 v2, v206, 0x3a800000, v217
	v_cmp_gt_f32_e64 s[0:1], s33, v2
	v_mul_f32_e32 v92, 0x4b800000, v2
	s_nop 0
	v_cndmask_b32_e64 v2, v2, v92, s[0:1]
	v_rsq_f32_e32 v2, v2
	s_nop 0
	v_mul_f32_e32 v92, 0x45800000, v2
	v_cndmask_b32_e64 v176, v2, v92, s[0:1]
	s_and_saveexec_b64 s[0:1], s[40:41]
	s_cbranch_execz .LBB0_102
	v_pk_mul_f32 v[94:95], v[66:67], v[176:177] op_sel_hi:[1,0]
	v_pk_mul_f32 v[92:93], v[64:65], v[176:177] op_sel_hi:[1,0]
	v_pk_mul_f32 v[96:97], v[62:63], v[176:177] op_sel_hi:[1,0]
	v_pk_mul_f32 v[98:99], v[60:61], v[176:177] op_sel_hi:[1,0]
	v_cvt_pk_bf16_f32 v92, v92, v93
	v_cvt_pk_bf16_f32 v93, v94, v95
	v_lshlrev_b32_e32 v2, 1, v100
	v_cvt_pk_bf16_f32 v94, v98, v99
	v_cvt_pk_bf16_f32 v95, v96, v97
	v_lshl_add_u32 v96, v188, 8, s11
	s_movk_i32 s16, 0xf200
	v_add3_u32 v2, v96, v2, s16
	ds_write_b128 v2, v[92:95]
.LBB0_102:
	s_or_b64 exec, exec, s[0:1]
	v_fmamk_f32 v2, v210, 0x3a800000, v217
	v_cmp_gt_f32_e64 s[0:1], s33, v2
	v_mul_f32_e32 v92, 0x4b800000, v2
	s_nop 0
	v_cndmask_b32_e64 v2, v2, v92, s[0:1]
	v_rsq_f32_e32 v2, v2
	s_nop 0
	v_mul_f32_e32 v92, 0x45800000, v2
	v_cndmask_b32_e64 v174, v2, v92, s[0:1]
	v_lshlrev_b32_e32 v2, 8, v188
	s_and_saveexec_b64 s[0:1], s[40:41]
	s_cbranch_execz .LBB0_104
	v_pk_mul_f32 v[94:95], v[50:51], v[174:175] op_sel_hi:[1,0]
	v_pk_mul_f32 v[92:93], v[48:49], v[174:175] op_sel_hi:[1,0]
	v_pk_mul_f32 v[96:97], v[46:47], v[174:175] op_sel_hi:[1,0]
	v_pk_mul_f32 v[98:99], v[44:45], v[174:175] op_sel_hi:[1,0]
	v_cvt_pk_bf16_f32 v92, v92, v93
	v_cvt_pk_bf16_f32 v93, v94, v95
	s_nop 0
	v_cvt_pk_bf16_f32 v94, v98, v99
	v_cvt_pk_bf16_f32 v95, v96, v97
	v_lshlrev_b32_e32 v96, 1, v100
	v_add3_u32 v96, s10, v2, v96
	ds_write_b128 v96, v[92:95] offset:1024
.LBB0_104:
	s_or_b64 exec, exec, s[0:1]
	v_fmamk_f32 v92, v214, 0x3a800000, v217
	v_cmp_gt_f32_e64 s[0:1], s33, v92
	v_mul_f32_e32 v93, 0x4b800000, v92
	s_nop 0
	v_cndmask_b32_e64 v92, v92, v93, s[0:1]
	v_rsq_f32_e32 v92, v92
	s_nop 0
	v_mul_f32_e32 v93, 0x45800000, v92
	v_cndmask_b32_e64 v172, v92, v93, s[0:1]
	s_and_saveexec_b64 s[0:1], s[40:41]
	s_cbranch_execz .LBB0_106
	v_pk_mul_f32 v[94:95], v[34:35], v[172:173] op_sel_hi:[1,0]
	v_pk_mul_f32 v[92:93], v[32:33], v[172:173] op_sel_hi:[1,0]
	v_pk_mul_f32 v[96:97], v[30:31], v[172:173] op_sel_hi:[1,0]
	v_pk_mul_f32 v[98:99], v[28:29], v[172:173] op_sel_hi:[1,0]
	v_cvt_pk_bf16_f32 v92, v92, v93
	v_cvt_pk_bf16_f32 v93, v94, v95
	s_nop 0
	v_cvt_pk_bf16_f32 v94, v98, v99
	v_cvt_pk_bf16_f32 v95, v96, v97
	v_lshlrev_b32_e32 v96, 1, v100
	v_add3_u32 v96, s10, v2, v96
	ds_write_b128 v96, v[92:95] offset:1536
.LBB0_106:
	s_or_b64 exec, exec, s[0:1]
	v_fmamk_f32 v84, v240, 0x3a800000, v217
	v_cmp_gt_f32_e64 s[0:1], s33, v84
	s_and_saveexec_b64 s[16:17], vcc
	s_xor_b64 s[16:17], exec, s[16:17]
	v_lshlrev_b32_e32 v1, 1, v100
	s_or_saveexec_b64 s[42:43], s[16:17]
	v_mul_f32_e32 v85, 0x4b800000, v84
	v_cndmask_b32_e64 v84, v84, v85, s[0:1]
	v_rsq_f32_e32 v84, v84
	s_nop 0
	v_mul_f32_e32 v85, 0x45800000, v84
	v_cndmask_b32_e64 v170, v84, v85, s[0:1]
	s_xor_b64 exec, exec, s[42:43]
	s_cbranch_execz .LBB0_110
	v_pk_mul_f32 v[86:87], v[18:19], v[170:171] op_sel_hi:[1,0]
	v_pk_mul_f32 v[84:85], v[16:17], v[170:171] op_sel_hi:[1,0]
	v_add3_u32 v2, s10, v2, v1
	v_pk_mul_f32 v[88:89], v[14:15], v[170:171] op_sel_hi:[1,0]
	v_pk_mul_f32 v[90:91], v[12:13], v[170:171] op_sel_hi:[1,0]
	v_cvt_pk_bf16_f32 v84, v84, v85
	v_cvt_pk_bf16_f32 v85, v86, v87
	s_nop 0
	v_cvt_pk_bf16_f32 v86, v90, v91
	v_cvt_pk_bf16_f32 v87, v88, v89
	ds_write_b128 v2, v[84:87] offset:2048

; __device__ __forceinline__ unsigned cvt_pk_bf16(float lo, float hi) { unsigned r; asm volatile("v_cvt_pk_bf16_f32 %0, %1, %2" : "=v"(r) : "v"(lo), "v"(hi)); return r; }
; __device__ __forceinline__ float row_rs(const float* ssq, int row, int fq) {
;     float s = 0.f;
; #pragma unroll
;     for (int i = 0; i < 4; ++i) s += ssq[(size_t)(fq * 4 + i) * T + row];
;     s += __shfl_xor(s, 16); s += __shfl_xor(s, 32);
;     return rsqrtf(s * (1.0f / D) + RMS_EPS);
; }
;     __device__ __forceinline__ void operator()(const f32x4 (&acc)[2][2][4][2], const Unit& u, int wr, int wc, int fr, int fq) const {
;     ...
;         for (int ai = 0; ai < 2; ++ai)
; #pragma unroll
;             for (int m = 0; m < 4; ++m) {
;                 const int row = row0 + ai * 128 + m * 16; const float rs = row_rs(ssq, row, fq);
;                 bf16* rowp = base + (size_t)row * ldc + ct;
; #pragma unroll
;                 for (int bj = 0; bj < 2; ++bj) {
;                     f32x4 v0 = acc[ai][bj][m][0] * rs + bv[bj][0], v1 = acc[ai][bj][m][1] * rs + bv[bj][1];
;                     if (isg) {
; #pragma unroll
;                         for (int e = 0; e < 4; ++e) { v0[e] = __builtin_amdgcn_rcpf(1.f + __expf(-v0[e])); v1[e] = __builtin_amdgcn_rcpf(1.f + __expf(-v1[e])); }
;                     }
;                     v4u w; w.x = pg8::cvt_pk_bf16(v0[0], v0[1]); w.y = pg8::cvt_pk_bf16(v0[2], v0[3]); w.z = pg8::cvt_pk_bf16(v1[0], v1[1]); w.w = pg8::cvt_pk_bf16(v1[2], v1[3]);
.LBB0_298:
	s_lshl_b32 s2, s93, 8
	v_cmp_lt_i32_e32 vcc, v225, v220
	s_add_i32 s2, s2, s62
	v_and_or_b32 v0, v219, 15, s2
	v_cndmask_b32_e32 v1, v219, v225, vcc
	v_cmp_lt_i32_e32 vcc, v226, v220
	v_lshlrev_b32_e32 v172, 2, v1
	v_lshlrev_b32_e32 v2, 19, v2
	v_cndmask_b32_e32 v1, v219, v226, vcc
	v_lshlrev_b32_e32 v173, 2, v1
	v_ashrrev_i32_e32 v1, 31, v0
	v_lshl_add_u64 v[154:155], v[0:1], 2, s[84:85]
	v_or_b32_e32 v160, 0x20000, v2
	v_mov_b32_e32 v161, v3
	v_lshl_add_u64 v[148:149], v[154:155], 0, v[2:3]
	v_lshl_add_u64 v[150:151], v[154:155], 0, v[160:161]
	v_or_b32_e32 v158, 0x40000, v2
	v_mov_b32_e32 v159, v3
	v_or_b32_e32 v156, 0x60000, v2
	v_mov_b32_e32 v157, v3
	v_lshl_add_u64 v[152:153], v[154:155], 0, v[158:159]
	v_lshl_add_u64 v[154:155], v[154:155], 0, v[156:157]
	v_lshl_add_u32 v196, v0, 2, v2
	v_add_u32_e32 v197, 0x20000, v196
	v_add_u32_e32 v198, 0x40000, v196
	v_add_u32_e32 v199, 0x60000, v196
	global_load_dword v174, v196, s[84:85]
	global_load_dword v175, v197, s[84:85]
	global_load_dword v176, v198, s[84:85]
	global_load_dword v177, v199, s[84:85]
	global_load_dword v178, v196, s[84:85] offset:64
	global_load_dword v179, v197, s[84:85] offset:64
	global_load_dword v180, v198, s[84:85] offset:64
	global_load_dword v181, v199, s[84:85] offset:64
	global_load_dword v182, v196, s[84:85] offset:128
	global_load_dword v183, v197, s[84:85] offset:128
	global_load_dword v184, v198, s[84:85] offset:128
	global_load_dword v185, v199, s[84:85] offset:128
	global_load_dword v186, v196, s[84:85] offset:192
	global_load_dword v187, v197, s[84:85] offset:192
	global_load_dword v188, v198, s[84:85] offset:192
	global_load_dword v189, v199, s[84:85] offset:192
	global_load_dword v190, v196, s[84:85] offset:512
	global_load_dword v191, v197, s[84:85] offset:512
	global_load_dword v204, v198, s[84:85] offset:512
	global_load_dword v205, v199, s[84:85] offset:512
	global_load_dword v206, v196, s[84:85] offset:576
	global_load_dword v207, v197, s[84:85] offset:576
	global_load_dword v208, v198, s[84:85] offset:576
	global_load_dword v209, v199, s[84:85] offset:576
	global_load_dword v210, v196, s[84:85] offset:640
	global_load_dword v211, v197, s[84:85] offset:640
	global_load_dword v200, v198, s[84:85] offset:640
	global_load_dword v201, v199, s[84:85] offset:640
	global_load_dword v202, v196, s[84:85] offset:704
	global_load_dword v203, v197, s[84:85] offset:704
	global_load_dword v212, v198, s[84:85] offset:704
	global_load_dword v213, v199, s[84:85] offset:704
	s_waitcnt vmcnt(0)
	v_add_f32_e32 v174, v174, v175
	v_add_f32_e32 v178, v178, v179
	v_add_f32_e32 v182, v182, v183
	v_add_f32_e32 v186, v186, v187
	v_add_f32_e32 v190, v190, v191
	v_add_f32_e32 v206, v206, v207
	v_add_f32_e32 v210, v210, v211
	v_add_f32_e32 v202, v202, v203
	v_add_f32_e32 v174, v174, v176
	v_add_f32_e32 v178, v178, v180
	v_add_f32_e32 v182, v182, v184
	v_add_f32_e32 v186, v186, v188
	v_add_f32_e32 v190, v190, v204
	v_add_f32_e32 v206, v206, v208
	v_add_f32_e32 v210, v210, v200
	v_add_f32_e32 v202, v202, v212
	v_add_f32_e32 v174, v174, v177
	v_add_f32_e32 v178, v178, v181
	v_add_f32_e32 v182, v182, v185
	v_add_f32_e32 v186, v186, v189
	v_add_f32_e32 v190, v190, v205
	v_add_f32_e32 v206, v206, v209
	v_add_f32_e32 v210, v210, v201
	v_add_f32_e32 v202, v202, v213
	ds_bpermute_b32 v175, v172, v174
	ds_bpermute_b32 v179, v172, v178
	ds_bpermute_b32 v183, v172, v182
	ds_bpermute_b32 v187, v172, v186
	ds_bpermute_b32 v191, v172, v190
	ds_bpermute_b32 v207, v172, v206
	ds_bpermute_b32 v211, v172, v210
	ds_bpermute_b32 v203, v172, v202
	s_waitcnt lgkmcnt(0)
	v_add_f32_e32 v174, v174, v175
	v_add_f32_e32 v178, v178, v179
	v_add_f32_e32 v182, v182, v183
	v_add_f32_e32 v186, v186, v187
	v_add_f32_e32 v190, v190, v191
	v_add_f32_e32 v206, v206, v207
	v_add_f32_e32 v210, v210, v211
	v_add_f32_e32 v202, v202, v203
	ds_bpermute_b32 v175, v173, v174
	ds_bpermute_b32 v179, v173, v178
	ds_bpermute_b32 v183, v173, v182
	ds_bpermute_b32 v187, v173, v186
	ds_bpermute_b32 v191, v173, v190
	ds_bpermute_b32 v207, v173, v206
	ds_bpermute_b32 v211, v173, v210
	ds_bpermute_b32 v203, v173, v202
	s_waitcnt lgkmcnt(0)
	v_add_f32_e32 v174, v174, v175
	v_add_f32_e32 v178, v178, v179
	v_add_f32_e32 v182, v182, v183
	v_add_f32_e32 v186, v186, v187
	v_add_f32_e32 v190, v190, v191
	v_add_f32_e32 v206, v206, v207
	v_add_f32_e32 v210, v210, v211
	v_add_f32_e32 v202, v202, v203
	v_fmamk_f32 v1, v174, 0x3a800000, v217
	v_cmp_gt_f32_e32 vcc, s33, v1
	v_mul_f32_e32 v164, 0x4b800000, v1
	s_nop 0
	v_cndmask_b32_e32 v1, v1, v164, vcc
	v_rsq_f32_e32 v1, v1
	s_nop 0
	v_mul_f32_e32 v164, 0x45800000, v1
	v_cndmask_b32_e32 v164, v1, v164, vcc
	v_pk_fma_f32 v[146:147], v[146:147], v[164:165], v[82:83] op_sel_hi:[1,0,1]
	v_pk_fma_f32 v[144:145], v[144:145], v[164:165], v[80:81] op_sel_hi:[1,0,1]
	v_pk_fma_f32 v[142:143], v[142:143], v[164:165], v[78:79] op_sel_hi:[1,0,1]
	v_pk_fma_f32 v[166:167], v[140:141], v[164:165], v[76:77] op_sel_hi:[1,0,1]
	s_and_b64 vcc, exec, s[40:41]
	s_cbranch_vccnz .LBB0_300
	v_mul_f32_e32 v1, 0xbfb8aa3b, v144
	v_exp_f32_e32 v1, v1
	v_mul_f32_e32 v140, 0xbfb8aa3b, v166
	v_exp_f32_e32 v140, v140
	v_mul_f32_e32 v141, 0xbfb8aa3b, v167
	v_add_f32_e32 v1, 1.0, v1
	v_rcp_f32_e32 v144, v1
	v_mul_f32_e32 v1, 0xbfb8aa3b, v145
	v_exp_f32_e32 v1, v1
	v_exp_f32_e32 v141, v141
	v_add_f32_e32 v140, 1.0, v140
	v_rcp_f32_e32 v166, v140
	v_add_f32_e32 v1, 1.0, v1
	v_mul_f32_e32 v140, 0xbfb8aa3b, v146
	v_rcp_f32_e32 v145, v1
	v_add_f32_e32 v1, 1.0, v141
	v_exp_f32_e32 v140, v140
	v_mul_f32_e32 v141, 0xbfb8aa3b, v142
	v_exp_f32_e32 v141, v141
	v_rcp_f32_e32 v167, v1
	v_add_f32_e32 v1, 1.0, v140
	v_mul_f32_e32 v140, 0xbfb8aa3b, v147
	v_rcp_f32_e32 v146, v1
	v_add_f32_e32 v1, 1.0, v141
	v_exp_f32_e32 v140, v140
	v_mul_f32_e32 v141, 0xbfb8aa3b, v143
	v_exp_f32_e32 v141, v141
	v_rcp_f32_e32 v142, v1
	v_add_f32_e32 v1, 1.0, v140
	v_rcp_f32_e32 v147, v1
	v_add_f32_e32 v1, 1.0, v141
	v_rcp_f32_e32 v143, v1

; __device__ __forceinline__ unsigned cvt_pk_bf16(float lo, float hi) { unsigned r; asm volatile("v_cvt_pk_bf16_f32 %0, %1, %2" : "=v"(r) : "v"(lo), "v"(hi)); return r; }
; __device__ __forceinline__ float row_rs(const float* ssq, int row, int fq) {
;     float s = 0.f;
; #pragma unroll
;     for (int i = 0; i < 4; ++i) s += ssq[(size_t)(fq * 4 + i) * T + row];
;     s += __shfl_xor(s, 16); s += __shfl_xor(s, 32);
;     return rsqrtf(s * (1.0f / D) + RMS_EPS);
; }
;     __device__ __forceinline__ void operator()(const f32x4 (&acc)[2][2][4][2], const Unit& u, int wr, int wc, int fr, int fq) const {
;     ...
;         for (int ai = 0; ai < 2; ++ai)
; #pragma unroll
;             for (int m = 0; m < 4; ++m) {
;                 const int row = row0 + ai * 128 + m * 16; const float rs = row_rs(ssq, row, fq);
;                 bf16* rowp = base + (size_t)row * ldc + ct;
; #pragma unroll
;                 for (int bj = 0; bj < 2; ++bj) {
;                     f32x4 v0 = acc[ai][bj][m][0] * rs + bv[bj][0], v1 = acc[ai][bj][m][1] * rs + bv[bj][1];
;                     if (isg) {
; #pragma unroll
;                         for (int e = 0; e < 4; ++e) { v0[e] = __builtin_amdgcn_rcpf(1.f + __expf(-v0[e])); v1[e] = __builtin_amdgcn_rcpf(1.f + __expf(-v1[e])); }
;                     }
;                     v4u w; w.x = pg8::cvt_pk_bf16(v0[0], v0[1]); w.y = pg8::cvt_pk_bf16(v0[2], v0[3]); w.z = pg8::cvt_pk_bf16(v1[0], v1[1]); w.w = pg8::cvt_pk_bf16(v1[2], v1[3]);
;                     __builtin_nontemporal_store(w, (v4u*)(rowp + bj * 32));
.LBB0_302:
	v_or_b32_e32 v142, 16, v0
	v_ashrrev_i32_e32 v143, 31, v142
	v_cvt_pk_bf16_f32 v136, v136, v137
	v_cvt_pk_bf16_f32 v137, v138, v139
	v_cvt_pk_bf16_f32 v138, v132, v133
	v_lshl_add_u64 v[132:133], s[84:85], 0, v[2:3]
	v_lshlrev_b64 v[144:145], 2, v[142:143]
	v_cvt_pk_bf16_f32 v139, v134, v135
	global_store_dwordx4 v[162:163], v[136:139], off offset:64 nt
	v_lshl_add_u64 v[134:135], v[132:133], 0, v[144:145]
	v_lshl_add_u64 v[134:135], s[84:85], 0, v[160:161]
	v_lshl_add_u64 v[136:137], v[134:135], 0, v[144:145]
	v_lshl_add_u64 v[136:137], s[84:85], 0, v[158:159]
	v_lshl_add_u64 v[138:139], v[136:137], 0, v[144:145]
	v_lshl_add_u64 v[138:139], s[84:85], 0, v[156:157]
	v_lshl_add_u64 v[144:145], v[138:139], 0, v[144:145]
	v_fmamk_f32 v1, v178, 0x3a800000, v217
	v_cmp_gt_f32_e32 vcc, s33, v1
	v_mul_f32_e32 v2, 0x4b800000, v1
	s_nop 0
	v_cndmask_b32_e32 v1, v1, v2, vcc
	v_rsq_f32_e32 v1, v1
	s_nop 0
	v_mul_f32_e32 v2, 0x45800000, v1
	v_cndmask_b32_e32 v144, v1, v2, vcc
	v_pk_fma_f32 v[130:131], v[130:131], v[144:145], v[82:83] op_sel_hi:[1,0,1]
	v_pk_fma_f32 v[128:129], v[128:129], v[144:145], v[80:81] op_sel_hi:[1,0,1]
	v_pk_fma_f32 v[126:127], v[126:127], v[144:145], v[78:79] op_sel_hi:[1,0,1]
	v_pk_fma_f32 v[124:125], v[124:125], v[144:145], v[76:77] op_sel_hi:[1,0,1]
	s_and_b64 vcc, exec, s[40:41]
	s_cbranch_vccnz .LBB0_304
	v_mul_f32_e32 v1, 0xbfb8aa3b, v128
	v_exp_f32_e32 v1, v1
	v_mul_f32_e32 v2, 0xbfb8aa3b, v124
	v_exp_f32_e32 v2, v2
	v_mul_f32_e32 v124, 0xbfb8aa3b, v125
	v_add_f32_e32 v1, 1.0, v1
	v_rcp_f32_e32 v128, v1
	v_mul_f32_e32 v1, 0xbfb8aa3b, v129
	v_exp_f32_e32 v1, v1
	v_exp_f32_e32 v125, v124
	v_add_f32_e32 v2, 1.0, v2
	v_rcp_f32_e32 v124, v2
	v_add_f32_e32 v1, 1.0, v1
	v_mul_f32_e32 v2, 0xbfb8aa3b, v130
	v_rcp_f32_e32 v129, v1
	v_add_f32_e32 v1, 1.0, v125
	v_exp_f32_e32 v2, v2
	v_mul_f32_e32 v125, 0xbfb8aa3b, v126
	v_exp_f32_e32 v126, v125
	v_rcp_f32_e32 v125, v1
	v_add_f32_e32 v1, 1.0, v2
	v_mul_f32_e32 v2, 0xbfb8aa3b, v131
	v_rcp_f32_e32 v130, v1
	v_add_f32_e32 v1, 1.0, v126
	v_exp_f32_e32 v2, v2
	v_mul_f32_e32 v126, 0xbfb8aa3b, v127
	v_exp_f32_e32 v127, v126
	v_rcp_f32_e32 v126, v1
	v_add_f32_e32 v1, 1.0, v2
	v_rcp_f32_e32 v131, v1
	v_add_f32_e32 v1, 1.0, v127
	v_rcp_f32_e32 v127, v1

; __device__ __forceinline__ unsigned cvt_pk_bf16(float lo, float hi) { unsigned r; asm volatile("v_cvt_pk_bf16_f32 %0, %1, %2" : "=v"(r) : "v"(lo), "v"(hi)); return r; }
; __device__ __forceinline__ float row_rs(const float* ssq, int row, int fq) {
;     float s = 0.f;
; #pragma unroll
;     for (int i = 0; i < 4; ++i) s += ssq[(size_t)(fq * 4 + i) * T + row];
;     s += __shfl_xor(s, 16); s += __shfl_xor(s, 32);
;     return rsqrtf(s * (1.0f / D) + RMS_EPS);
; }
;     __device__ __forceinline__ void operator()(const f32x4 (&acc)[2][2][4][2], const Unit& u, int wr, int wc, int fr, int fq) const {
;     ...
;         for (int ai = 0; ai < 2; ++ai)
; #pragma unroll
;             for (int m = 0; m < 4; ++m) {
;                 const int row = row0 + ai * 128 + m * 16; const float rs = row_rs(ssq, row, fq);
;                 bf16* rowp = base + (size_t)row * ldc + ct;
; #pragma unroll
;                 for (int bj = 0; bj < 2; ++bj) {
;                     f32x4 v0 = acc[ai][bj][m][0] * rs + bv[bj][0], v1 = acc[ai][bj][m][1] * rs + bv[bj][1];
;                     if (isg) {
; #pragma unroll
;                         for (int e = 0; e < 4; ++e) { v0[e] = __builtin_amdgcn_rcpf(1.f + __expf(-v0[e])); v1[e] = __builtin_amdgcn_rcpf(1.f + __expf(-v1[e])); }
;                     }
;                     v4u w; w.x = pg8::cvt_pk_bf16(v0[0], v0[1]); w.y = pg8::cvt_pk_bf16(v0[2], v0[3]); w.z = pg8::cvt_pk_bf16(v1[0], v1[1]); w.w = pg8::cvt_pk_bf16(v1[2], v1[3]);
;                     __builtin_nontemporal_store(w, (v4u*)(rowp + bj * 32));
.LBB0_306:
	v_cvt_pk_bf16_f32 v120, v120, v121
	v_cvt_pk_bf16_f32 v121, v122, v123
	v_cvt_pk_bf16_f32 v122, v116, v117
	v_or_b32_e32 v116, 32, v0
	v_ashrrev_i32_e32 v117, 31, v116
	v_cvt_pk_bf16_f32 v123, v118, v119
	v_lshlrev_b64 v[118:119], 2, v[116:117]
	global_store_dwordx4 v[142:143], v[120:123], off offset:64 nt
	v_lshl_add_u64 v[124:125], v[136:137], 0, v[118:119]
	s_and_b64 vcc, exec, s[40:41]
	v_lshl_add_u64 v[120:121], v[132:133], 0, v[118:119]
	v_lshl_add_u64 v[122:123], v[134:135], 0, v[118:119]
	v_lshl_add_u64 v[118:119], v[138:139], 0, v[118:119]
	v_fmamk_f32 v1, v182, 0x3a800000, v217
	v_mul_f32_e32 v2, 0x4b800000, v1
	v_cmp_gt_f32_e64 s[0:1], s33, v1
	s_nop 1
	v_cndmask_b32_e64 v1, v1, v2, s[0:1]
	v_rsq_f32_e32 v1, v1
	s_nop 0
	v_mul_f32_e32 v2, 0x45800000, v1
	v_cndmask_b32_e64 v118, v1, v2, s[0:1]
	v_pk_fma_f32 v[114:115], v[114:115], v[118:119], v[82:83] op_sel_hi:[1,0,1]
	v_pk_fma_f32 v[112:113], v[112:113], v[118:119], v[80:81] op_sel_hi:[1,0,1]
	v_pk_fma_f32 v[110:111], v[110:111], v[118:119], v[78:79] op_sel_hi:[1,0,1]
	v_pk_fma_f32 v[120:121], v[108:109], v[118:119], v[76:77] op_sel_hi:[1,0,1]
	s_cbranch_vccnz .LBB0_308
	v_mul_f32_e32 v1, 0xbfb8aa3b, v112
	v_exp_f32_e32 v1, v1
	v_mul_f32_e32 v2, 0xbfb8aa3b, v120
	v_exp_f32_e32 v2, v2
	v_mul_f32_e32 v108, 0xbfb8aa3b, v121
	v_add_f32_e32 v1, 1.0, v1
	v_rcp_f32_e32 v112, v1
	v_mul_f32_e32 v1, 0xbfb8aa3b, v113
	v_exp_f32_e32 v1, v1
	v_exp_f32_e32 v108, v108
	v_add_f32_e32 v2, 1.0, v2
	v_rcp_f32_e32 v120, v2
	v_add_f32_e32 v1, 1.0, v1
	v_mul_f32_e32 v2, 0xbfb8aa3b, v114
	v_rcp_f32_e32 v113, v1
	v_add_f32_e32 v1, 1.0, v108
	v_exp_f32_e32 v2, v2
	v_mul_f32_e32 v108, 0xbfb8aa3b, v110
	v_exp_f32_e32 v108, v108
	v_rcp_f32_e32 v121, v1
	v_add_f32_e32 v1, 1.0, v2
	v_mul_f32_e32 v2, 0xbfb8aa3b, v115
	v_rcp_f32_e32 v114, v1
	v_add_f32_e32 v1, 1.0, v108
	v_exp_f32_e32 v2, v2
	v_mul_f32_e32 v108, 0xbfb8aa3b, v111
	v_exp_f32_e32 v108, v108
	v_rcp_f32_e32 v110, v1
	v_add_f32_e32 v1, 1.0, v2
	v_rcp_f32_e32 v115, v1
	v_add_f32_e32 v1, 1.0, v108
	v_rcp_f32_e32 v111, v1

; __device__ __forceinline__ unsigned cvt_pk_bf16(float lo, float hi) { unsigned r; asm volatile("v_cvt_pk_bf16_f32 %0, %1, %2" : "=v"(r) : "v"(lo), "v"(hi)); return r; }
; __device__ __forceinline__ float row_rs(const float* ssq, int row, int fq) {
;     float s = 0.f;
; #pragma unroll
;     for (int i = 0; i < 4; ++i) s += ssq[(size_t)(fq * 4 + i) * T + row];
;     s += __shfl_xor(s, 16); s += __shfl_xor(s, 32);
;     return rsqrtf(s * (1.0f / D) + RMS_EPS);
; }
;     __device__ __forceinline__ void operator()(const f32x4 (&acc)[2][2][4][2], const Unit& u, int wr, int wc, int fr, int fq) const {
;     ...
;         for (int ai = 0; ai < 2; ++ai)
; #pragma unroll
;             for (int m = 0; m < 4; ++m) {
;                 const int row = row0 + ai * 128 + m * 16; const float rs = row_rs(ssq, row, fq);
;                 bf16* rowp = base + (size_t)row * ldc + ct;
; #pragma unroll
;                 for (int bj = 0; bj < 2; ++bj) {
;                     f32x4 v0 = acc[ai][bj][m][0] * rs + bv[bj][0], v1 = acc[ai][bj][m][1] * rs + bv[bj][1];
;                     if (isg) {
; #pragma unroll
;                         for (int e = 0; e < 4; ++e) { v0[e] = __builtin_amdgcn_rcpf(1.f + __expf(-v0[e])); v1[e] = __builtin_amdgcn_rcpf(1.f + __expf(-v1[e])); }
;                     }
;                     v4u w; w.x = pg8::cvt_pk_bf16(v0[0], v0[1]); w.y = pg8::cvt_pk_bf16(v0[2], v0[3]); w.z = pg8::cvt_pk_bf16(v1[0], v1[1]); w.w = pg8::cvt_pk_bf16(v1[2], v1[3]);
;                     __builtin_nontemporal_store(w, (v4u*)(rowp + bj * 32));
.LBB0_310:
	v_cvt_pk_bf16_f32 v104, v104, v105
	v_cvt_pk_bf16_f32 v105, v106, v107
	v_cvt_pk_bf16_f32 v106, v100, v101
	v_or_b32_e32 v100, 48, v0
	v_ashrrev_i32_e32 v101, 31, v100
	v_cvt_pk_bf16_f32 v107, v102, v103
	v_lshlrev_b64 v[102:103], 2, v[100:101]
	global_store_dwordx4 v[108:109], v[104:107], off offset:64 nt
	v_lshl_add_u64 v[108:109], v[136:137], 0, v[102:103]
	s_and_b64 vcc, exec, s[40:41]
	v_lshl_add_u64 v[104:105], v[132:133], 0, v[102:103]
	v_lshl_add_u64 v[106:107], v[134:135], 0, v[102:103]
	v_lshl_add_u64 v[102:103], v[138:139], 0, v[102:103]
	v_fmamk_f32 v1, v186, 0x3a800000, v217
	v_mul_f32_e32 v2, 0x4b800000, v1
	v_cmp_gt_f32_e64 s[0:1], s33, v1
	s_nop 1
	v_cndmask_b32_e64 v1, v1, v2, s[0:1]
	v_rsq_f32_e32 v1, v1
	s_nop 0
	v_mul_f32_e32 v2, 0x45800000, v1
	v_cndmask_b32_e64 v102, v1, v2, s[0:1]
	v_pk_fma_f32 v[98:99], v[98:99], v[102:103], v[82:83] op_sel_hi:[1,0,1]
	v_pk_fma_f32 v[96:97], v[96:97], v[102:103], v[80:81] op_sel_hi:[1,0,1]
	v_pk_fma_f32 v[94:95], v[94:95], v[102:103], v[78:79] op_sel_hi:[1,0,1]
	v_pk_fma_f32 v[104:105], v[92:93], v[102:103], v[76:77] op_sel_hi:[1,0,1]
	s_cbranch_vccnz .LBB0_312
	v_mul_f32_e32 v1, 0xbfb8aa3b, v96
	v_exp_f32_e32 v1, v1
	v_mul_f32_e32 v2, 0xbfb8aa3b, v104
	v_exp_f32_e32 v2, v2
	v_mul_f32_e32 v92, 0xbfb8aa3b, v105
	v_add_f32_e32 v1, 1.0, v1
	v_rcp_f32_e32 v96, v1
	v_mul_f32_e32 v1, 0xbfb8aa3b, v97
	v_exp_f32_e32 v1, v1
	v_exp_f32_e32 v92, v92
	v_add_f32_e32 v2, 1.0, v2
	v_rcp_f32_e32 v104, v2
	v_add_f32_e32 v1, 1.0, v1
	v_mul_f32_e32 v2, 0xbfb8aa3b, v98
	v_rcp_f32_e32 v97, v1
	v_add_f32_e32 v1, 1.0, v92
	v_exp_f32_e32 v2, v2
	v_mul_f32_e32 v92, 0xbfb8aa3b, v94
	v_exp_f32_e32 v92, v92
	v_rcp_f32_e32 v105, v1
	v_add_f32_e32 v1, 1.0, v2
	v_mul_f32_e32 v2, 0xbfb8aa3b, v99
	v_rcp_f32_e32 v98, v1
	v_add_f32_e32 v1, 1.0, v92
	v_exp_f32_e32 v2, v2
	v_mul_f32_e32 v92, 0xbfb8aa3b, v95
	v_exp_f32_e32 v92, v92
	v_rcp_f32_e32 v94, v1
	v_add_f32_e32 v1, 1.0, v2
	v_rcp_f32_e32 v99, v1
	v_add_f32_e32 v1, 1.0, v92
	v_rcp_f32_e32 v95, v1

; __device__ __forceinline__ unsigned cvt_pk_bf16(float lo, float hi) { unsigned r; asm volatile("v_cvt_pk_bf16_f32 %0, %1, %2" : "=v"(r) : "v"(lo), "v"(hi)); return r; }
; __device__ __forceinline__ float row_rs(const float* ssq, int row, int fq) {
;     float s = 0.f;
; #pragma unroll
;     for (int i = 0; i < 4; ++i) s += ssq[(size_t)(fq * 4 + i) * T + row];
;     s += __shfl_xor(s, 16); s += __shfl_xor(s, 32);
;     return rsqrtf(s * (1.0f / D) + RMS_EPS);
; }
;     __device__ __forceinline__ void operator()(const f32x4 (&acc)[2][2][4][2], const Unit& u, int wr, int wc, int fr, int fq) const {
;     ...
;         for (int ai = 0; ai < 2; ++ai)
; #pragma unroll
;             for (int m = 0; m < 4; ++m) {
;                 const int row = row0 + ai * 128 + m * 16; const float rs = row_rs(ssq, row, fq);
;                 bf16* rowp = base + (size_t)row * ldc + ct;
; #pragma unroll
;                 for (int bj = 0; bj < 2; ++bj) {
;                     f32x4 v0 = acc[ai][bj][m][0] * rs + bv[bj][0], v1 = acc[ai][bj][m][1] * rs + bv[bj][1];
;                     if (isg) {
; #pragma unroll
;                         for (int e = 0; e < 4; ++e) { v0[e] = __builtin_amdgcn_rcpf(1.f + __expf(-v0[e])); v1[e] = __builtin_amdgcn_rcpf(1.f + __expf(-v1[e])); }
;                     }
;                     v4u w; w.x = pg8::cvt_pk_bf16(v0[0], v0[1]); w.y = pg8::cvt_pk_bf16(v0[2], v0[3]); w.z = pg8::cvt_pk_bf16(v1[0], v1[1]); w.w = pg8::cvt_pk_bf16(v1[2], v1[3]);
;                     __builtin_nontemporal_store(w, (v4u*)(rowp + bj * 32));
.LBB0_314:
	v_cvt_pk_bf16_f32 v88, v88, v89
	v_cvt_pk_bf16_f32 v89, v90, v91
	v_cvt_pk_bf16_f32 v90, v84, v85
	v_cvt_pk_bf16_f32 v91, v86, v87
	global_store_dwordx4 v[92:93], v[88:91], off offset:64 nt
	s_and_b64 vcc, exec, s[40:41]
	v_fmamk_f32 v1, v190, 0x3a800000, v217
	v_mul_f32_e32 v2, 0x4b800000, v1
	v_cmp_gt_f32_e64 s[0:1], s33, v1
	s_nop 1
	v_cndmask_b32_e64 v1, v1, v2, s[0:1]
	v_rsq_f32_e32 v1, v1
	s_nop 0
	v_mul_f32_e32 v2, 0x45800000, v1
	v_cndmask_b32_e64 v84, v1, v2, s[0:1]
	v_pk_fma_f32 v[74:75], v[74:75], v[84:85], v[82:83] op_sel_hi:[1,0,1]
	v_pk_fma_f32 v[72:73], v[72:73], v[84:85], v[80:81] op_sel_hi:[1,0,1]
	v_pk_fma_f32 v[66:67], v[66:67], v[84:85], v[78:79] op_sel_hi:[1,0,1]
	v_pk_fma_f32 v[86:87], v[64:65], v[84:85], v[76:77] op_sel_hi:[1,0,1]
	s_cbranch_vccnz .LBB0_316
	v_mul_f32_e32 v1, 0xbfb8aa3b, v72
	v_exp_f32_e32 v1, v1
	v_mul_f32_e32 v2, 0xbfb8aa3b, v86
	v_exp_f32_e32 v2, v2
	v_mul_f32_e32 v64, 0xbfb8aa3b, v87
	v_add_f32_e32 v1, 1.0, v1
	v_rcp_f32_e32 v72, v1
	v_mul_f32_e32 v1, 0xbfb8aa3b, v73
	v_exp_f32_e32 v1, v1
	v_exp_f32_e32 v64, v64
	v_add_f32_e32 v2, 1.0, v2
	v_rcp_f32_e32 v86, v2
	v_add_f32_e32 v1, 1.0, v1
	v_mul_f32_e32 v2, 0xbfb8aa3b, v74
	v_rcp_f32_e32 v73, v1
	v_add_f32_e32 v1, 1.0, v64
	v_exp_f32_e32 v2, v2
	v_mul_f32_e32 v64, 0xbfb8aa3b, v66
	v_exp_f32_e32 v64, v64
	v_rcp_f32_e32 v87, v1
	v_add_f32_e32 v1, 1.0, v2
	v_mul_f32_e32 v2, 0xbfb8aa3b, v75
	v_rcp_f32_e32 v74, v1
	v_add_f32_e32 v1, 1.0, v64
	v_exp_f32_e32 v2, v2
	v_mul_f32_e32 v64, 0xbfb8aa3b, v67
	v_exp_f32_e32 v64, v64
	v_rcp_f32_e32 v66, v1
	v_add_f32_e32 v1, 1.0, v2
	v_rcp_f32_e32 v75, v1
	v_add_f32_e32 v1, 1.0, v64
	v_rcp_f32_e32 v67, v1

; __device__ __forceinline__ unsigned cvt_pk_bf16(float lo, float hi) { unsigned r; asm volatile("v_cvt_pk_bf16_f32 %0, %1, %2" : "=v"(r) : "v"(lo), "v"(hi)); return r; }
; __device__ __forceinline__ float row_rs(const float* ssq, int row, int fq) {
;     float s = 0.f;
; #pragma unroll
;     for (int i = 0; i < 4; ++i) s += ssq[(size_t)(fq * 4 + i) * T + row];
;     s += __shfl_xor(s, 16); s += __shfl_xor(s, 32);
;     return rsqrtf(s * (1.0f / D) + RMS_EPS);
; }
;     __device__ __forceinline__ void operator()(const f32x4 (&acc)[2][2][4][2], const Unit& u, int wr, int wc, int fr, int fq) const {
;     ...
;         for (int ai = 0; ai < 2; ++ai)
; #pragma unroll
;             for (int m = 0; m < 4; ++m) {
;                 const int row = row0 + ai * 128 + m * 16; const float rs = row_rs(ssq, row, fq);
;                 bf16* rowp = base + (size_t)row * ldc + ct;
; #pragma unroll
;                 for (int bj = 0; bj < 2; ++bj) {
;                     f32x4 v0 = acc[ai][bj][m][0] * rs + bv[bj][0], v1 = acc[ai][bj][m][1] * rs + bv[bj][1];
;                     if (isg) {
; #pragma unroll
;                         for (int e = 0; e < 4; ++e) { v0[e] = __builtin_amdgcn_rcpf(1.f + __expf(-v0[e])); v1[e] = __builtin_amdgcn_rcpf(1.f + __expf(-v1[e])); }
;                     }
;                     v4u w; w.x = pg8::cvt_pk_bf16(v0[0], v0[1]); w.y = pg8::cvt_pk_bf16(v0[2], v0[3]); w.z = pg8::cvt_pk_bf16(v1[0], v1[1]); w.w = pg8::cvt_pk_bf16(v1[2], v1[3]);
;                     __builtin_nontemporal_store(w, (v4u*)(rowp + bj * 32));
.LBB0_318:
	v_cvt_pk_bf16_f32 v56, v56, v57
	v_cvt_pk_bf16_f32 v57, v58, v59
	v_cvt_pk_bf16_f32 v58, v52, v53
	v_cvt_pk_bf16_f32 v59, v54, v55
	global_store_dwordx4 v[64:65], v[56:59], off offset:64 nt
	s_and_b64 vcc, exec, s[40:41]
	v_fmamk_f32 v1, v206, 0x3a800000, v217
	v_mul_f32_e32 v2, 0x4b800000, v1
	v_cmp_gt_f32_e64 s[0:1], s33, v1
	s_nop 1
	v_cndmask_b32_e64 v1, v1, v2, s[0:1]
	v_rsq_f32_e32 v1, v1
	s_nop 0
	v_mul_f32_e32 v2, 0x45800000, v1
	v_cndmask_b32_e64 v52, v1, v2, s[0:1]
	v_pk_fma_f32 v[50:51], v[50:51], v[52:53], v[82:83] op_sel_hi:[1,0,1]
	v_pk_fma_f32 v[48:49], v[48:49], v[52:53], v[80:81] op_sel_hi:[1,0,1]
	v_pk_fma_f32 v[46:47], v[46:47], v[52:53], v[78:79] op_sel_hi:[1,0,1]
	v_pk_fma_f32 v[54:55], v[44:45], v[52:53], v[76:77] op_sel_hi:[1,0,1]
	s_cbranch_vccnz .LBB0_320
	v_mul_f32_e32 v1, 0xbfb8aa3b, v48
	v_exp_f32_e32 v1, v1
	v_mul_f32_e32 v2, 0xbfb8aa3b, v54
	v_exp_f32_e32 v2, v2
	v_mul_f32_e32 v44, 0xbfb8aa3b, v55
	v_add_f32_e32 v1, 1.0, v1
	v_rcp_f32_e32 v48, v1
	v_mul_f32_e32 v1, 0xbfb8aa3b, v49
	v_exp_f32_e32 v1, v1
	v_exp_f32_e32 v44, v44
	v_add_f32_e32 v2, 1.0, v2
	v_rcp_f32_e32 v54, v2
	v_add_f32_e32 v1, 1.0, v1
	v_mul_f32_e32 v2, 0xbfb8aa3b, v50
	v_rcp_f32_e32 v49, v1
	v_add_f32_e32 v1, 1.0, v44
	v_exp_f32_e32 v2, v2
	v_mul_f32_e32 v44, 0xbfb8aa3b, v46
	v_exp_f32_e32 v44, v44
	v_rcp_f32_e32 v55, v1
	v_add_f32_e32 v1, 1.0, v2
	v_mul_f32_e32 v2, 0xbfb8aa3b, v51
	v_rcp_f32_e32 v50, v1
	v_add_f32_e32 v1, 1.0, v44
	v_exp_f32_e32 v2, v2
	v_mul_f32_e32 v44, 0xbfb8aa3b, v47
	v_exp_f32_e32 v44, v44
	v_rcp_f32_e32 v46, v1
	v_add_f32_e32 v1, 1.0, v2
	v_rcp_f32_e32 v51, v1
	v_add_f32_e32 v1, 1.0, v44
	v_rcp_f32_e32 v47, v1

; __device__ __forceinline__ unsigned cvt_pk_bf16(float lo, float hi) { unsigned r; asm volatile("v_cvt_pk_bf16_f32 %0, %1, %2" : "=v"(r) : "v"(lo), "v"(hi)); return r; }
; __device__ __forceinline__ float row_rs(const float* ssq, int row, int fq) {
;     float s = 0.f;
; #pragma unroll
;     for (int i = 0; i < 4; ++i) s += ssq[(size_t)(fq * 4 + i) * T + row];
;     s += __shfl_xor(s, 16); s += __shfl_xor(s, 32);
;     return rsqrtf(s * (1.0f / D) + RMS_EPS);
; }
;     __device__ __forceinline__ void operator()(const f32x4 (&acc)[2][2][4][2], const Unit& u, int wr, int wc, int fr, int fq) const {
;     ...
;         for (int ai = 0; ai < 2; ++ai)
; #pragma unroll
;             for (int m = 0; m < 4; ++m) {
;                 const int row = row0 + ai * 128 + m * 16; const float rs = row_rs(ssq, row, fq);
;                 bf16* rowp = base + (size_t)row * ldc + ct;
; #pragma unroll
;                 for (int bj = 0; bj < 2; ++bj) {
;                     f32x4 v0 = acc[ai][bj][m][0] * rs + bv[bj][0], v1 = acc[ai][bj][m][1] * rs + bv[bj][1];
;                     if (isg) {
; #pragma unroll
;                         for (int e = 0; e < 4; ++e) { v0[e] = __builtin_amdgcn_rcpf(1.f + __expf(-v0[e])); v1[e] = __builtin_amdgcn_rcpf(1.f + __expf(-v1[e])); }
;                     }
;                     v4u w; w.x = pg8::cvt_pk_bf16(v0[0], v0[1]); w.y = pg8::cvt_pk_bf16(v0[2], v0[3]); w.z = pg8::cvt_pk_bf16(v1[0], v1[1]); w.w = pg8::cvt_pk_bf16(v1[2], v1[3]);
;                     __builtin_nontemporal_store(w, (v4u*)(rowp + bj * 32));
.LBB0_322:
	v_cvt_pk_bf16_f32 v40, v40, v41
	v_cvt_pk_bf16_f32 v41, v42, v43
	v_cvt_pk_bf16_f32 v42, v36, v37
	v_cvt_pk_bf16_f32 v43, v38, v39
	global_store_dwordx4 v[44:45], v[40:43], off offset:64 nt
	s_and_b64 vcc, exec, s[40:41]
	v_fmamk_f32 v1, v210, 0x3a800000, v217
	v_mul_f32_e32 v2, 0x4b800000, v1
	v_cmp_gt_f32_e64 s[0:1], s33, v1
	s_nop 1
	v_cndmask_b32_e64 v1, v1, v2, s[0:1]
	v_rsq_f32_e32 v1, v1
	s_nop 0
	v_mul_f32_e32 v2, 0x45800000, v1
	v_cndmask_b32_e64 v36, v1, v2, s[0:1]
	v_pk_fma_f32 v[34:35], v[34:35], v[36:37], v[82:83] op_sel_hi:[1,0,1]
	v_pk_fma_f32 v[32:33], v[32:33], v[36:37], v[80:81] op_sel_hi:[1,0,1]
	v_pk_fma_f32 v[30:31], v[30:31], v[36:37], v[78:79] op_sel_hi:[1,0,1]
	v_pk_fma_f32 v[38:39], v[28:29], v[36:37], v[76:77] op_sel_hi:[1,0,1]
	s_cbranch_vccnz .LBB0_324
	v_mul_f32_e32 v1, 0xbfb8aa3b, v32
	v_exp_f32_e32 v1, v1
	v_mul_f32_e32 v2, 0xbfb8aa3b, v38
	v_exp_f32_e32 v2, v2
	v_mul_f32_e32 v28, 0xbfb8aa3b, v39
	v_add_f32_e32 v1, 1.0, v1
	v_rcp_f32_e32 v32, v1
	v_mul_f32_e32 v1, 0xbfb8aa3b, v33
	v_exp_f32_e32 v1, v1
	v_exp_f32_e32 v28, v28
	v_add_f32_e32 v2, 1.0, v2
	v_rcp_f32_e32 v38, v2
	v_add_f32_e32 v1, 1.0, v1
	v_mul_f32_e32 v2, 0xbfb8aa3b, v34
	v_rcp_f32_e32 v33, v1
	v_add_f32_e32 v1, 1.0, v28
	v_exp_f32_e32 v2, v2
	v_mul_f32_e32 v28, 0xbfb8aa3b, v30
	v_exp_f32_e32 v28, v28
	v_rcp_f32_e32 v39, v1
	v_add_f32_e32 v1, 1.0, v2
	v_mul_f32_e32 v2, 0xbfb8aa3b, v35
	v_rcp_f32_e32 v34, v1
	v_add_f32_e32 v1, 1.0, v28
	v_exp_f32_e32 v2, v2
	v_mul_f32_e32 v28, 0xbfb8aa3b, v31
	v_exp_f32_e32 v28, v28
	v_rcp_f32_e32 v30, v1
	v_add_f32_e32 v1, 1.0, v2
	v_rcp_f32_e32 v35, v1
	v_add_f32_e32 v1, 1.0, v28
	v_rcp_f32_e32 v31, v1

; __device__ __forceinline__ unsigned cvt_pk_bf16(float lo, float hi) { unsigned r; asm volatile("v_cvt_pk_bf16_f32 %0, %1, %2" : "=v"(r) : "v"(lo), "v"(hi)); return r; }
; __device__ __forceinline__ float row_rs(const float* ssq, int row, int fq) {
;     float s = 0.f;
; #pragma unroll
;     for (int i = 0; i < 4; ++i) s += ssq[(size_t)(fq * 4 + i) * T + row];
;     s += __shfl_xor(s, 16); s += __shfl_xor(s, 32);
;     return rsqrtf(s * (1.0f / D) + RMS_EPS);
; }
;     __device__ __forceinline__ void operator()(const f32x4 (&acc)[2][2][4][2], const Unit& u, int wr, int wc, int fr, int fq) const {
;     ...
;         for (int ai = 0; ai < 2; ++ai)
; #pragma unroll
;             for (int m = 0; m < 4; ++m) {
;                 const int row = row0 + ai * 128 + m * 16; const float rs = row_rs(ssq, row, fq);
;                 bf16* rowp = base + (size_t)row * ldc + ct;
; #pragma unroll
;                 for (int bj = 0; bj < 2; ++bj) {
;                     f32x4 v0 = acc[ai][bj][m][0] * rs + bv[bj][0], v1 = acc[ai][bj][m][1] * rs + bv[bj][1];
;                     if (isg) {
; #pragma unroll
;                         for (int e = 0; e < 4; ++e) { v0[e] = __builtin_amdgcn_rcpf(1.f + __expf(-v0[e])); v1[e] = __builtin_amdgcn_rcpf(1.f + __expf(-v1[e])); }
;                     }
;                     v4u w; w.x = pg8::cvt_pk_bf16(v0[0], v0[1]); w.y = pg8::cvt_pk_bf16(v0[2], v0[3]); w.z = pg8::cvt_pk_bf16(v1[0], v1[1]); w.w = pg8::cvt_pk_bf16(v1[2], v1[3]);
;                     __builtin_nontemporal_store(w, (v4u*)(rowp + bj * 32));
.LBB0_326:
	v_cvt_pk_bf16_f32 v24, v24, v25
	v_cvt_pk_bf16_f32 v25, v26, v27
	v_cvt_pk_bf16_f32 v26, v20, v21
	v_cvt_pk_bf16_f32 v27, v22, v23
	global_store_dwordx4 v[28:29], v[24:27], off offset:64 nt
	s_and_b64 vcc, exec, s[40:41]
	v_fmamk_f32 v1, v202, 0x3a800000, v217
	v_mul_f32_e32 v2, 0x4b800000, v1
	v_cmp_gt_f32_e64 s[0:1], s33, v1
	s_nop 1
	v_cndmask_b32_e64 v1, v1, v2, s[0:1]
	v_rsq_f32_e32 v1, v1
	s_nop 0
	v_mul_f32_e32 v2, 0x45800000, v1
	v_cndmask_b32_e64 v20, v1, v2, s[0:1]
	v_pk_fma_f32 v[18:19], v[18:19], v[20:21], v[82:83] op_sel_hi:[1,0,1]
	v_pk_fma_f32 v[16:17], v[16:17], v[20:21], v[80:81] op_sel_hi:[1,0,1]
	v_pk_fma_f32 v[14:15], v[14:15], v[20:21], v[78:79] op_sel_hi:[1,0,1]
	v_pk_fma_f32 v[12:13], v[12:13], v[20:21], v[76:77] op_sel_hi:[1,0,1]
	s_cbranch_vccnz .LBB0_328
	v_mul_f32_e32 v1, 0xbfb8aa3b, v16
	v_exp_f32_e32 v1, v1
	v_mul_f32_e32 v2, 0xbfb8aa3b, v12
	v_exp_f32_e32 v2, v2
	v_mul_f32_e32 v12, 0xbfb8aa3b, v13
	v_add_f32_e32 v1, 1.0, v1
	v_rcp_f32_e32 v16, v1
	v_mul_f32_e32 v1, 0xbfb8aa3b, v17
	v_exp_f32_e32 v1, v1
	v_exp_f32_e32 v13, v12
	v_add_f32_e32 v2, 1.0, v2
	v_rcp_f32_e32 v12, v2
	v_add_f32_e32 v1, 1.0, v1
	v_mul_f32_e32 v2, 0xbfb8aa3b, v18
	v_rcp_f32_e32 v17, v1
	v_add_f32_e32 v1, 1.0, v13
	v_exp_f32_e32 v2, v2
	v_mul_f32_e32 v13, 0xbfb8aa3b, v14
	v_exp_f32_e32 v14, v13
	v_rcp_f32_e32 v13, v1
	v_add_f32_e32 v1, 1.0, v2
	v_mul_f32_e32 v2, 0xbfb8aa3b, v19
	v_rcp_f32_e32 v18, v1
	v_add_f32_e32 v1, 1.0, v14
	v_exp_f32_e32 v2, v2
	v_mul_f32_e32 v14, 0xbfb8aa3b, v15
	v_exp_f32_e32 v15, v14
	v_rcp_f32_e32 v14, v1
	v_add_f32_e32 v1, 1.0, v2
	v_rcp_f32_e32 v19, v1
	v_add_f32_e32 v1, 1.0, v15
	v_rcp_f32_e32 v15, v1
